# as before plus the out-projection phase: workgroups without a sample split-K unit and with bit 3 of their id set start two sleeps late
# speedup vs baseline: 1.0029x; 1.0029x over previous
;     __host__ __device__ bool next(int i, Unit& u) const { return at((long)i * G + c, u); }
;     __device__ bool next(int i, Unit& u) const { const long L = (long)i * G + c; if (L >= 128) return false; u.pm = 64 + (int)(L >> 6); u.pn = (int)(L >> 4) & 3; u.kofs = ((int)L & 15) * 256; return true; }
;     __device__ bool next(int i, Unit& u) const { const long L = (long)i * G + c; if (L >= 32) return false; u.pm = 64 + (int)(L >> 4); u.pn = (int)(L >> 2) & 3; u.kofs = ((int)L & 3) * 256; return true; }
; template <class Epi, class Sched, bool ALIGN_EPI = false, bool SP2 = false>
; __device__ __forceinline__ void gemm_phase(PG8_LAS unsigned char* lds, const Gemm g, const Sched& S, const Epi& E) {
;     ...
;     Unit cur, nxt; int ui = 0;
;     if (!S.next(0, cur)) return;
; __global__ void __launch_bounds__(NWAVES * 64, 2) hymba_fwd(Args A) {
;     ...
;         pg8::Gemm g{(const pg8::bf16_t*)(ws + WS_MIX), (const pg8::bf16_t*)(ws + WS_W2), NPROMPT, DM, DM, DM};
;         pg8::StaticOrder S; S.init(NPROMPT, DM, G, bx);
;         pg8::EpiRes<true> E{A.in[0], A.in[1], ROW_SAMP, A.out, (pg8::bf16_t*)(ws + WS_X1B), (float*)(ws + WS_SS2)};
;         pg8::gemm_phase<pg8::EpiRes<true>, pg8::StaticOrder, true, true>(lds, g, S, E);
;         pg8::Gemm g2{(const pg8::bf16_t*)(ws + WS_MIX), (const pg8::bf16_t*)(ws + WS_W2), M2, DM, 256, DM};
;         pg8::SplitK4Order S2{G, bx};
;         pg8::EpiP3S E2{(float*)(ws + WS_XA), A.in[1], A.out, (pg8::bf16_t*)(ws + WS_X1B), (float*)(ws + WS_SS2), (unsigned*)ws + 8192};
;         pg8::gemm_phase<pg8::EpiP3S, pg8::SplitK4Order, false, true>(lds, g2, S2, E2);
.LBB0_593:
	s_or_b64 exec, exec, s[0:1]
	v_readlane_b32 s0, v250, 51
	v_readlane_b32 s1, v250, 52
	v_mov_b32_e32 v8, v138
	s_waitcnt lgkmcnt(0)
	v_cndmask_b32_e64 v0, 0, 1, s[0:1]
	s_barrier
	s_cmp_lt_u32 s22, 32
	s_cbranch_scc1 .Lstag_p3
	s_bitcmp1_b32 s22, 3
	s_cbranch_scc0 .Lstag_p3
	s_sleep 127
	s_sleep 127
.Lstag_p3:
	v_cmp_ne_u32_e64 s[2:3], 1, v0
	s_andn2_b64 vcc, exec, s[0:1]
	v_readfirstlane_b32 s6, v8
	s_cbranch_vccnz .LBB0_599
	s_ashr_i32 s0, s22, 31
	s_lshr_b32 s0, s0, 29
	s_add_i32 s4, s22, s0
	s_and_b32 s0, s4, -8
	s_sub_i32 s5, s22, s0
	s_cmp_gt_i32 s5, -1
	s_cbranch_scc0 .LBB0_596
	s_lshl_b32 s7, s5, 5
	s_cbranch_execz .LBB0_597
	s_branch .LBB0_598
